# pool mixer: the second unit's nine global loads are prefetched into spare registers right after the first unit's header barrier
# baseline (speedup 1.0000x reference)
; #define LAS __attribute__((address_space(3)))
; __device__ __forceinline__ void pool_unit(LAS unsigned char* lds, int unit, const bf16* P0, const bf16* PWt, const float* pscale, bf16* MIX) {
;     int tid = threadIdx.x; asm volatile("" : "+v"(tid)); const int lane = tid & 63, wave = tid >> 6, li = lane & 15, g = lane >> 4;
;     const int grp = unit < 256 ? (unit & 3) : 3 - (unit & 3), rt = unit >> 2, row0 = rt * 128, tt0 = row0 & 8191;
;     LAS unsigned char* Al = lds; LAS unsigned char* Bl = lds + 128 * RS; LAS unsigned char* Ul = lds + 256 * RS;
; __global__ void __launch_bounds__(NTHR, 2) fwd_megakernel(Args args) {
;     ...
;     for (int u = blockIdx.x; u < 512; u += G) pool_unit(lds, u, P0, (const bf16*)(ws + WS_POOLW), args.in[9], MIX);
.LBB0_227:
	s_add_u32 s2, s10, 0x9800000
	s_addc_u32 s3, s11, 0
	s_cmpk_gt_i32 s91, 0x1ff
	s_cbranch_scc1 .LBB0_261
	s_lshl_b32 s18, s91, 5
	s_lshl_b32 s19, s6, 5
	s_mov_b32 s51, 0
	v_mov_b32_e32 v57, 0
	s_movk_i32 s70, 0x1800
	s_movk_i32 s71, 0x110
	s_add_i32 s74, 0, 0x11000
	s_mov_b32 s75, s91
	s_mov_b32 s32, 0
	s_branch .LBB0_231

; #define LAS __attribute__((address_space(3)))
; __device__ __forceinline__ void pool_unit(LAS unsigned char* lds, int unit, const bf16* P0, const bf16* PWt, const float* pscale, bf16* MIX) {
;     int tid = threadIdx.x; asm volatile("" : "+v"(tid)); const int lane = tid & 63, wave = tid >> 6, li = lane & 15, g = lane >> 4;
;     const int grp = unit < 256 ? (unit & 3) : 3 - (unit & 3), rt = unit >> 2, row0 = rt * 128, tt0 = row0 & 8191;
;     LAS unsigned char* Al = lds; LAS unsigned char* Bl = lds + 128 * RS; LAS unsigned char* Ul = lds + 256 * RS;
;     {
;         const bf16* src = PWt + (size_t)grp * 16384;
;         v4u bw[4], uw[5];
; #pragma unroll
;         for (int j = 0; j < 4; ++j) { const int i = tid + NTHR * j, d = i >> 4, c16 = i & 15; bw[j] = *(const v4u*)(src + d * 128 + c16 * 8); }
; #pragma unroll
;         for (int j = 0; j < 5; ++j) { const int i = tid + NTHR * j, r = i >> 4, c16 = i & 15; const int tt = tt0 - 15 + r;
;             uw[j] = (v4u){0u, 0u, 0u, 0u};
;             if (i < 143 * 16 && tt >= 0) uw[j] = *(const v4u*)(P0 + (size_t)(row0 - 15 + r) * N0 + 2048 + grp * 128 + c16 * 8); }
; #pragma unroll
;         for (int j = 0; j < 4; ++j) { const int i = tid + NTHR * j, d = i >> 4, c16 = i & 15; *(LAS v4u*)(Bl + d * RS + c16 * 16) = bw[j]; }
; #pragma unroll
;         for (int j = 0; j < 5; ++j) { const int i = tid + NTHR * j, r = i >> 4, c16 = i & 15; if (i < 143 * 16) *(LAS v4u*)(Ul + r * RS + c16 * 16) = uw[j]; }
.LBB0_231:
	s_and_b32 s0, s75, 3
	s_xor_b32 s1, s0, 3
	s_cmpk_lt_i32 s75, 0x100
	v_mov_b32_e32 v92, v216
	s_cselect_b32 s84, s0, s1
	s_and_b32 s76, s18, 0xffffff80
	s_lshl_b32 s0, s84, 15
	v_lshlrev_b32_e32 v0, 3, v92
	s_add_u32 s0, s46, s0
	v_and_b32_e32 v1, 0x78, v0
	s_addc_u32 s1, s47, 0
	v_lshlrev_b32_e32 v56, 1, v1
	v_and_b32_e32 v10, 0xffffff80, v0
	v_lshl_add_u64 v[8:9], s[0:1], 0, v[56:57]
	v_ashrrev_i32_e32 v11, 31, v10
	v_lshl_add_u64 v[0:1], v[10:11], 1, v[8:9]
	v_add_u32_e32 v2, 0x1000, v10
	v_add_u32_e32 v12, 0x2000, v10
	v_add_u32_e32 v10, 0x3000, v10
	v_ashrrev_i32_e32 v3, 31, v2
	v_ashrrev_i32_e32 v13, 31, v12
	v_ashrrev_i32_e32 v11, 31, v10
	v_lshl_add_u64 v[2:3], v[2:3], 1, v[8:9]
	v_lshl_add_u64 v[12:13], v[12:13], 1, v[8:9]
	v_lshl_add_u64 v[8:9], v[10:11], 1, v[8:9]
	s_cmp_eq_u32 s32, 1
	s_cbranch_scc1 .Lpp_sk0
	global_load_dwordx4 v[4:7], v[0:1], off
	s_nop 0
	global_load_dwordx4 v[0:3], v[2:3], off
	s_nop 0
	global_load_dwordx4 v[12:15], v[12:13], off
	s_nop 0
	global_load_dwordx4 v[8:11], v[8:9], off
.Lpp_sk0:
	s_and_b32 s5, s18, 0x1f80
	s_sub_i32 s17, 14, s5
	s_waitcnt vmcnt(12)
	v_ashrrev_i32_e32 v36, 4, v92
	s_movk_i32 s0, 0x8f0
	v_cmp_gt_i32_e64 s[36:37], s0, v92
	v_cmp_lt_i32_e32 vcc, s17, v36
	s_add_i32 s16, s76, -15
	s_lshl_b32 s77, s84, 7
	s_and_b64 s[14:15], s[36:37], vcc
	v_mov_b32_e32 v16, v57
	v_mov_b32_e32 v17, v57
	v_mov_b32_e32 v18, v57
	v_mov_b32_e32 v19, v57
	s_and_saveexec_b64 s[0:1], s[14:15]
	s_cbranch_execz .LBB0_233
	v_add_u32_e32 v18, s16, v36
	v_mov_b64_e32 v[16:17], s[20:21]
	v_mad_i64_i32 v[16:17], s[14:15], v18, s70, v[16:17]
	s_lshl_b32 s50, s77, 1
	v_lshl_add_u64 v[16:17], v[16:17], 0, s[50:51]
	v_lshl_add_u64 v[16:17], v[16:17], 0, v[56:57]
	v_add_co_u32_e32 v16, vcc, 0x1000, v16
	s_nop 1
	v_addc_co_u32_e32 v17, vcc, 0, v17, vcc
	s_cmp_eq_u32 s32, 1
	s_cbranch_scc1 .Lpp_sk1
	global_load_dwordx4 v[16:19], v[16:17], off
.Lpp_sk1:
.LBB0_233:
	s_or_b64 exec, exec, s[0:1]
	v_add_u32_e32 v20, 0x200, v92
	v_ashrrev_i32_e32 v37, 4, v20
	s_movk_i32 s0, 0x6f0
	v_cmp_gt_i32_e64 s[38:39], s0, v92
	v_cmp_lt_i32_e32 vcc, s17, v37
	s_and_b64 s[14:15], s[38:39], vcc
	v_mov_b32_e32 v20, 0
	v_mov_b32_e32 v24, 0
	v_mov_b32_e32 v25, 0
	v_mov_b32_e32 v26, 0
	v_mov_b32_e32 v27, 0
	s_and_saveexec_b64 s[0:1], s[14:15]
	s_cbranch_execz .LBB0_235
	v_add_u32_e32 v21, s16, v37
	v_mov_b64_e32 v[22:23], s[20:21]
	v_mad_i64_i32 v[22:23], s[14:15], v21, s70, v[22:23]
	s_lshl_b32 s50, s77, 1
	v_lshl_add_u64 v[22:23], v[22:23], 0, s[50:51]
	v_lshl_add_u64 v[22:23], v[22:23], 0, v[56:57]
	v_add_co_u32_e32 v22, vcc, 0x1000, v22
	s_nop 1
	v_addc_co_u32_e32 v23, vcc, 0, v23, vcc
	s_cmp_eq_u32 s32, 1
	s_cbranch_scc1 .Lpp_sk2
	global_load_dwordx4 v[24:27], v[22:23], off
.Lpp_sk2:
.LBB0_235:
	s_or_b64 exec, exec, s[0:1]
	v_add_u32_e32 v21, 0x400, v92
	v_ashrrev_i32_e32 v38, 4, v21
	s_movk_i32 s0, 0x4f0
	v_cmp_gt_i32_e64 s[40:41], s0, v92
	v_cmp_lt_i32_e32 vcc, s17, v38
	s_and_b64 s[14:15], s[40:41], vcc
	v_mov_b32_e32 v21, 0
	v_mov_b32_e32 v22, 0
	v_mov_b32_e32 v23, 0
	s_and_saveexec_b64 s[0:1], s[14:15]
	s_cbranch_execz .LBB0_237
	v_add_u32_e32 v22, s16, v38
	v_mov_b64_e32 v[20:21], s[20:21]
	v_mad_i64_i32 v[20:21], s[14:15], v22, s70, v[20:21]
	s_lshl_b32 s50, s77, 1
	v_lshl_add_u64 v[20:21], v[20:21], 0, s[50:51]
	v_lshl_add_u64 v[20:21], v[20:21], 0, v[56:57]
	v_add_co_u32_e32 v20, vcc, 0x1000, v20
	s_nop 1
	v_addc_co_u32_e32 v21, vcc, 0, v21, vcc
	s_cmp_eq_u32 s32, 1
	s_cbranch_scc1 .Lpp_sk3
	global_load_dwordx4 v[20:23], v[20:21], off
.Lpp_sk3:
.LBB0_237:
	s_or_b64 exec, exec, s[0:1]
	v_add_u32_e32 v28, 0x600, v92
	v_ashrrev_i32_e32 v40, 4, v28
	s_movk_i32 s0, 0x2f0
	v_cmp_gt_i32_e64 s[42:43], s0, v92
	v_cmp_lt_i32_e32 vcc, s17, v40
	s_and_b64 s[14:15], s[42:43], vcc
	v_mov_b32_e32 v28, 0
	v_mov_b32_e32 v32, 0
	v_mov_b32_e32 v33, 0
	v_mov_b32_e32 v34, 0
	v_mov_b32_e32 v35, 0
	s_and_saveexec_b64 s[0:1], s[14:15]
	s_cbranch_execz .LBB0_239
	v_add_u32_e32 v29, s16, v40
	v_mov_b64_e32 v[30:31], s[20:21]
	v_mad_i64_i32 v[30:31], s[14:15], v29, s70, v[30:31]
	s_lshl_b32 s50, s77, 1
	v_lshl_add_u64 v[30:31], v[30:31], 0, s[50:51]
	v_lshl_add_u64 v[30:31], v[30:31], 0, v[56:57]
	v_add_co_u32_e32 v30, vcc, 0x1000, v30
	s_nop 1
	v_addc_co_u32_e32 v31, vcc, 0, v31, vcc
	s_cmp_eq_u32 s32, 1
	s_cbranch_scc1 .Lpp_sk4
	global_load_dwordx4 v[32:35], v[30:31], off
.Lpp_sk4:
.LBB0_239:
	s_or_b64 exec, exec, s[0:1]
	v_add_u32_e32 v29, 0x800, v92
	v_ashrrev_i32_e32 v39, 4, v29
	s_movk_i32 s0, 0xf0
	v_cmp_gt_i32_e64 s[44:45], s0, v92
	v_cmp_lt_i32_e32 vcc, s17, v39
	s_and_b64 s[14:15], s[44:45], vcc
	v_mov_b32_e32 v29, 0
	v_mov_b32_e32 v30, 0
	v_mov_b32_e32 v31, 0
	s_and_saveexec_b64 s[0:1], s[14:15]
	s_cbranch_execz .LBB0_241
	v_add_u32_e32 v30, s16, v39
	v_mov_b64_e32 v[28:29], s[20:21]
	v_mad_i64_i32 v[28:29], s[14:15], v30, s70, v[28:29]
	s_lshl_b32 s50, s77, 1
	v_lshl_add_u64 v[28:29], v[28:29], 0, s[50:51]
	v_lshl_add_u64 v[28:29], v[28:29], 0, v[56:57]
	v_add_co_u32_e32 v28, vcc, 0x1000, v28
	s_nop 1
	v_addc_co_u32_e32 v29, vcc, 0, v29, vcc
	s_cmp_eq_u32 s32, 1
	s_cbranch_scc1 .Lpp_sk5
	global_load_dwordx4 v[28:31], v[28:29], off
.Lpp_sk5:
.LBB0_241:
	s_or_b64 exec, exec, s[0:1]
	v_lshlrev_b32_e32 v41, 4, v92
	v_and_b32_e32 v41, 0xf0, v41
	v_add_u32_e32 v42, 0, v41
	v_mul_lo_u32 v36, v36, s71
	v_add_u32_e32 v43, v42, v36
	s_cmp_eq_u32 s32, 1
	s_cbranch_scc0 .Lpp_nomov
	v_mov_b64_e32 v[4:5], v[156:157]
	v_mov_b64_e32 v[6:7], v[158:159]
	v_mov_b64_e32 v[0:1], v[160:161]
	v_mov_b64_e32 v[2:3], v[162:163]
	v_mov_b64_e32 v[12:13], v[164:165]
	v_mov_b64_e32 v[14:15], v[166:167]
	v_mov_b64_e32 v[8:9], v[168:169]
	v_mov_b64_e32 v[10:11], v[170:171]
	v_mov_b64_e32 v[16:17], v[172:173]
	v_mov_b64_e32 v[18:19], v[174:175]
	v_mov_b64_e32 v[24:25], v[176:177]
	v_mov_b64_e32 v[26:27], v[178:179]
	v_mov_b64_e32 v[20:21], v[180:181]
	v_mov_b64_e32 v[22:23], v[182:183]
	v_mov_b64_e32 v[32:33], v[184:185]
	v_mov_b64_e32 v[34:35], v[186:187]
	v_mov_b64_e32 v[28:29], v[188:189]
	v_mov_b64_e32 v[30:31], v[190:191]
	s_mov_b32 s32, 0
.Lpp_nomov:
	s_waitcnt vmcnt(3)
	ds_write_b128 v43, v[4:7] offset:34816
	v_mul_lo_u32 v4, v37, s71
	v_add_u32_e32 v5, v42, v4
	s_waitcnt vmcnt(2)
	ds_write_b128 v5, v[0:3] offset:34816
	v_mul_lo_u32 v2, v38, s71
	v_add_u32_e32 v0, v42, v2
	v_mul_lo_u32 v1, v40, s71
	s_waitcnt vmcnt(1)
	ds_write_b128 v0, v[12:15] offset:34816
	v_add_u32_e32 v0, v42, v1
	s_waitcnt vmcnt(0)
	ds_write_b128 v0, v[8:11] offset:34816
	v_add_u32_e32 v0, s74, v41
	s_and_saveexec_b64 s[0:1], s[36:37]
	s_cbranch_execz .LBB0_250
	v_add_u32_e32 v3, v0, v36
	ds_write_b128 v3, v[16:19]
	s_or_b64 exec, exec, s[0:1]
	s_and_saveexec_b64 s[0:1], s[38:39]
	s_cbranch_execnz .LBB0_251

; #define LAS __attribute__((address_space(3)))
; __device__ __forceinline__ float bflo(unsigned w) { return __uint_as_float(w << 16); }
; __device__ __forceinline__ float bfhi(unsigned w) { return __uint_as_float(w & 0xffff0000u); }
; template <int W> __device__ __forceinline__ void pool_fill(LAS unsigned char* Al, const LAS unsigned char* Ul, int tid, int tt0) {
;     const int t = tid >> 2, cq = tid & 3; const int tt = tt0 + t; const int cnt = tt + 1 < W ? tt + 1 : W;
;     const float inv = 1.0f / (float)cnt;
; #pragma unroll
;     for (int ch = 0; ch < 4; ++ch) {
;         float acc[8];
; #pragma unroll
;         for (int e = 0; e < 8; ++e) acc[e] = 0.f;
;         v4u self = (v4u){0u, 0u, 0u, 0u};
; #pragma unroll
;         for (int j = 0; j < W; ++j) { const v4u x = *(const LAS v4u*)(Ul + (t + 15 - j) * RS + (cq * 32 + ch * 8) * 2); if (j == 0) self = x;
; #pragma unroll
;             for (int e = 0; e < 4; ++e) { acc[2 * e] += bflo(x[e]); acc[2 * e + 1] += bfhi(x[e]); } }
; __device__ __forceinline__ void pool_unit(LAS unsigned char* lds, int unit, const bf16* P0, const bf16* PWt, const float* pscale, bf16* MIX) {
;     ...
;     __syncthreads();
;     if (grp == 0) pool_fill<2>(Al, Ul, tid, tt0); else if (grp == 1) pool_fill<4>(Al, Ul, tid, tt0); else if (grp == 2) pool_fill<8>(Al, Ul, tid, tt0); else pool_fill<16>(Al, Ul, tid, tt0);
.LBB0_247:
	s_or_b64 exec, exec, s[0:1]
	v_ashrrev_i32_e32 v56, 2, v92
	v_lshlrev_b32_e32 v0, 6, v92
	v_and_b32_e32 v93, 0xc0, v0
	v_mul_lo_u32 v8, v56, s71
	v_add3_u32 v49, s74, v93, v8
	s_waitcnt lgkmcnt(0)
	s_barrier
	s_add_i32 s98, s75, s6
	s_cmpk_gt_i32 s98, 0x1ff
	s_cbranch_scc1 .Lpp_none
	s_and_b32 s99, s98, 3
	s_xor_b32 s100, s99, 3
	s_cmpk_lt_i32 s98, 0x100
	s_cselect_b32 s99, s99, s100
	s_add_i32 s98, s18, s19
	s_and_b32 s85, s98, 0x1f80
	s_sub_i32 s85, 14, s85
	s_and_b32 s98, s98, 0xffffff80
	s_lshl_b32 s100, s99, 15
	s_add_u32 s100, s46, s100
	s_addc_u32 s101, s47, 0
	v_lshlrev_b32_e32 v192, 4, v216
	global_load_dwordx4 v[156:159], v192, s[100:101]
	s_add_u32 s100, s100, 0x2000
	s_addc_u32 s101, s101, 0
	global_load_dwordx4 v[160:163], v192, s[100:101]
	s_add_u32 s100, s100, 0x2000
	s_addc_u32 s101, s101, 0
	global_load_dwordx4 v[164:167], v192, s[100:101]
	s_add_u32 s100, s100, 0x2000
	s_addc_u32 s101, s101, 0
	global_load_dwordx4 v[168:171], v192, s[100:101]
	s_add_i32 s98, s98, -15
	s_mul_i32 s88, s98, 0x1800
	s_mul_hi_i32 s89, s98, 0x1800
	s_lshl_b32 s90, s99, 8
	s_add_u32 s88, s88, s90
	s_addc_u32 s89, s89, 0
	s_add_u32 s88, s88, 0x1000
	s_addc_u32 s89, s89, 0
	s_add_u32 s88, s88, s20
	s_addc_u32 s89, s89, s21
	v_lshrrev_b32_e32 v193, 4, v216
	v_and_b32_e32 v194, 15, v216
	v_lshlrev_b32_e32 v194, 4, v194
	v_mad_u32_u24 v194, v193, s70, v194
	v_mov_b32_e32 v172, 0
	v_mov_b32_e32 v173, 0
	v_mov_b32_e32 v174, 0
	v_mov_b32_e32 v175, 0
	v_mov_b32_e32 v188, 0
	v_mov_b32_e32 v189, 0
	v_mov_b32_e32 v190, 0
	v_mov_b32_e32 v191, 0
	v_cmp_lt_i32_e64 s[24:25], s85, v193
	s_nop 1
	s_and_saveexec_b64 s[100:101], s[24:25]
	global_load_dwordx4 v[172:175], v194, s[88:89]
	s_mov_b64 exec, s[100:101]
	s_add_u32 s88, s88, 0x30000
	s_addc_u32 s89, s89, 0
	global_load_dwordx4 v[176:179], v194, s[88:89]
	s_add_u32 s88, s88, 0x30000
	s_addc_u32 s89, s89, 0
	global_load_dwordx4 v[180:183], v194, s[88:89]
	s_add_u32 s88, s88, 0x30000
	s_addc_u32 s89, s89, 0
	global_load_dwordx4 v[184:187], v194, s[88:89]
	s_add_u32 s88, s88, 0x30000
	s_addc_u32 s89, s89, 0
	s_movk_i32 s22, 0xf0
	v_cmp_gt_u32_e64 s[24:25], s22, v216
	s_nop 1
	s_and_saveexec_b64 s[100:101], s[24:25]
	global_load_dwordx4 v[188:191], v194, s[88:89]
	s_mov_b64 exec, s[100:101]
	s_mov_b32 s32, 1
.Lpp_none:
	ds_read_b128 v[0:3], v49 offset:4080
	ds_read_b128 v[4:7], v49 offset:3808
	v_add_u32_e32 v94, 0, v8
	v_add_u32_e32 v95, s5, v56
	s_cmp_lt_i32 s84, 2
	s_waitcnt lgkmcnt(1)
	v_lshlrev_b32_e32 v54, 16, v1
	v_and_b32_e32 v55, 0xffff0000, v1
	v_lshlrev_b32_e32 v58, 16, v0
	v_and_b32_e32 v59, 0xffff0000, v0
	s_waitcnt lgkmcnt(0)
	v_lshlrev_b32_e32 v10, 16, v4
	v_and_b32_e32 v11, 0xffff0000, v4
	v_pk_add_f32 v[0:1], v[54:55], 0 op_sel_hi:[1,0]
	v_lshlrev_b32_e32 v4, 16, v5
	v_and_b32_e32 v5, 0xffff0000, v5
	v_lshlrev_b32_e32 v52, 16, v2
	v_and_b32_e32 v53, 0xffff0000, v2
	v_pk_add_f32 v[64:65], v[0:1], v[4:5]
	v_pk_add_f32 v[0:1], v[52:53], 0 op_sel_hi:[1,0]
	v_lshlrev_b32_e32 v4, 16, v6
	v_and_b32_e32 v5, 0xffff0000, v6
	v_lshlrev_b32_e32 v50, 16, v3
	v_and_b32_e32 v51, 0xffff0000, v3
	v_pk_add_f32 v[8:9], v[58:59], 0 op_sel_hi:[1,0]
	v_pk_add_f32 v[62:63], v[0:1], v[4:5]
	v_pk_add_f32 v[0:1], v[50:51], 0 op_sel_hi:[1,0]
	v_lshlrev_b32_e32 v2, 16, v7
	v_and_b32_e32 v3, 0xffff0000, v7
	v_pk_add_f32 v[66:67], v[8:9], v[10:11]
	v_pk_add_f32 v[60:61], v[0:1], v[2:3]
	s_mov_b64 s[0:1], -1
	s_cbranch_scc1 .LBB0_257
	s_cmp_gt_i32 s84, 2
	s_cbranch_scc0 .LBB0_254
	v_min_i32_e32 v0, 15, v95
	v_add_u32_e32 v0, 1, v0
	v_cvt_f32_i32_e32 v0, v0
	v_add_u32_e32 v116, v94, v93
	v_div_scale_f32 v1, s[0:1], v0, v0, 1.0
	v_rcp_f32_e32 v2, v1
	s_nop 0
	v_fma_f32 v3, -v1, v2, 1.0
	v_fmac_f32_e32 v2, v3, v2
	v_div_scale_f32 v3, vcc, 1.0, v0, 1.0
	v_mul_f32_e32 v4, v3, v2
	v_fma_f32 v5, -v1, v4, v3
	v_fmac_f32_e32 v4, v5, v2
	v_fma_f32 v1, -v1, v4, v3
	v_div_fmas_f32 v1, v1, v2, v4
	v_div_fixup_f32 v48, v1, v0, 1.0
	ds_read_b128 v[0:3], v49 offset:3536
	ds_read_b128 v[4:7], v49 offset:3264
	ds_read_b128 v[8:11], v49 offset:2992
	ds_read_b128 v[12:15], v49 offset:2720
	ds_read_b128 v[16:19], v49 offset:2448
	s_waitcnt lgkmcnt(4)
	v_lshlrev_b32_e32 v20, 16, v0
	v_and_b32_e32 v21, 0xffff0000, v0
	v_lshlrev_b32_e32 v0, 16, v1
	v_and_b32_e32 v1, 0xffff0000, v1
	s_waitcnt lgkmcnt(3)
	v_lshlrev_b32_e32 v22, 16, v4
	v_and_b32_e32 v23, 0xffff0000, v4
	v_pk_add_f32 v[0:1], v[64:65], v[0:1]
	v_lshlrev_b32_e32 v4, 16, v5
	v_and_b32_e32 v5, 0xffff0000, v5
	v_pk_add_f32 v[0:1], v[0:1], v[4:5]
	s_waitcnt lgkmcnt(2)
	v_lshlrev_b32_e32 v4, 16, v9
	v_and_b32_e32 v5, 0xffff0000, v9
	v_pk_add_f32 v[0:1], v[0:1], v[4:5]
	s_waitcnt lgkmcnt(1)
	v_lshlrev_b32_e32 v4, 16, v13
	v_and_b32_e32 v5, 0xffff0000, v13
	v_pk_add_f32 v[0:1], v[0:1], v[4:5]
	s_waitcnt lgkmcnt(0)
	v_lshlrev_b32_e32 v4, 16, v17
	v_and_b32_e32 v5, 0xffff0000, v17
	v_pk_add_f32 v[30:31], v[0:1], v[4:5]
	v_lshlrev_b32_e32 v0, 16, v2
	v_and_b32_e32 v1, 0xffff0000, v2
	v_pk_add_f32 v[0:1], v[62:63], v[0:1]
	v_lshlrev_b32_e32 v4, 16, v6
	v_and_b32_e32 v5, 0xffff0000, v6
	v_pk_add_f32 v[0:1], v[0:1], v[4:5]
	v_lshlrev_b32_e32 v4, 16, v10
	v_and_b32_e32 v5, 0xffff0000, v10
	v_pk_add_f32 v[0:1], v[0:1], v[4:5]
	v_lshlrev_b32_e32 v4, 16, v14
	v_and_b32_e32 v5, 0xffff0000, v14
	v_pk_add_f32 v[0:1], v[0:1], v[4:5]
	v_lshlrev_b32_e32 v4, 16, v18
	v_and_b32_e32 v5, 0xffff0000, v18
	v_pk_add_f32 v[32:33], v[0:1], v[4:5]
	v_lshlrev_b32_e32 v0, 16, v3
	v_and_b32_e32 v1, 0xffff0000, v3
	v_pk_add_f32 v[0:1], v[60:61], v[0:1]
	v_lshlrev_b32_e32 v2, 16, v7
	v_and_b32_e32 v3, 0xffff0000, v7
	v_pk_add_f32 v[0:1], v[0:1], v[2:3]
	v_lshlrev_b32_e32 v2, 16, v11
	v_and_b32_e32 v3, 0xffff0000, v11
	v_pk_add_f32 v[0:1], v[0:1], v[2:3]
	v_lshlrev_b32_e32 v2, 16, v15
	v_and_b32_e32 v3, 0xffff0000, v15
	v_pk_add_f32 v[0:1], v[0:1], v[2:3]
	v_lshlrev_b32_e32 v2, 16, v19
	v_and_b32_e32 v3, 0xffff0000, v19
	v_pk_add_f32 v[34:35], v[0:1], v[2:3]
	ds_read_b128 v[0:3], v49 offset:2176
	v_pk_add_f32 v[20:21], v[66:67], v[20:21]
	s_waitcnt lgkmcnt(0)
; #define LAS __attribute__((address_space(3)))
; __device__ __forceinline__ unsigned pk2(float lo, float hi) { f32x2_t v = {lo, hi}; bf16x2_t b = __builtin_convertvector(v, bf16x2_t); return __builtin_bit_cast(unsigned, b); }
; __device__ __forceinline__ float bflo(unsigned w) { return __uint_as_float(w << 16); }
; __device__ __forceinline__ float bfhi(unsigned w) { return __uint_as_float(w & 0xffff0000u); }
; template <int W> __device__ __forceinline__ void pool_fill(LAS unsigned char* Al, const LAS unsigned char* Ul, int tid, int tt0) {
;     ...
;     for (int ch = 0; ch < 4; ++ch) {
;         float acc[8];
; #pragma unroll
;         for (int e = 0; e < 8; ++e) acc[e] = 0.f;
;         v4u self = (v4u){0u, 0u, 0u, 0u};
; #pragma unroll
;         for (int j = 0; j < W; ++j) { const v4u x = *(const LAS v4u*)(Ul + (t + 15 - j) * RS + (cq * 32 + ch * 8) * 2); if (j == 0) self = x;
; #pragma unroll
;             for (int e = 0; e < 4; ++e) { acc[2 * e] += bflo(x[e]); acc[2 * e + 1] += bfhi(x[e]); } }
;         v4u o;
; #pragma unroll
;         for (int e = 0; e < 4; ++e) o[e] = pk2(acc[2 * e] * inv - bflo(self[e]), acc[2 * e + 1] * inv - bfhi(self[e]));
;         *(LAS v4u*)(Al + t * RS + (cq * 32 + ch * 8) * 2) = o;
;     }
	v_lshlrev_b32_e32 v36, 16, v0
	v_and_b32_e32 v37, 0xffff0000, v0
	v_lshlrev_b32_e32 v38, 16, v1
	v_and_b32_e32 v39, 0xffff0000, v1
	v_lshlrev_b32_e32 v40, 16, v2
	v_and_b32_e32 v41, 0xffff0000, v2
	v_lshlrev_b32_e32 v42, 16, v3
	v_and_b32_e32 v43, 0xffff0000, v3
	ds_read_b128 v[0:3], v49 offset:1904
	v_pk_add_f32 v[20:21], v[20:21], v[22:23]
	v_lshlrev_b32_e32 v22, 16, v8
	v_and_b32_e32 v23, 0xffff0000, v8
	v_pk_add_f32 v[20:21], v[20:21], v[22:23]
	s_waitcnt lgkmcnt(0)
	v_lshlrev_b32_e32 v44, 16, v0
	v_and_b32_e32 v45, 0xffff0000, v0
	v_lshlrev_b32_e32 v46, 16, v1
	v_and_b32_e32 v47, 0xffff0000, v1
	v_lshlrev_b32_e32 v68, 16, v2
	v_and_b32_e32 v69, 0xffff0000, v2
	v_lshlrev_b32_e32 v70, 16, v3
	v_and_b32_e32 v71, 0xffff0000, v3
	ds_read_b128 v[0:3], v49 offset:1632
	v_lshlrev_b32_e32 v22, 16, v12
	v_and_b32_e32 v23, 0xffff0000, v12
	v_pk_add_f32 v[20:21], v[20:21], v[22:23]
	v_lshlrev_b32_e32 v22, 16, v16
	v_and_b32_e32 v23, 0xffff0000, v16
	v_pk_add_f32 v[28:29], v[20:21], v[22:23]
	s_waitcnt lgkmcnt(0)
	v_lshlrev_b32_e32 v72, 16, v0
	v_pk_add_f32 v[28:29], v[28:29], v[36:37]
	v_and_b32_e32 v73, 0xffff0000, v0
	v_pk_add_f32 v[28:29], v[28:29], v[44:45]
	v_lshlrev_b32_e32 v74, 16, v1
	v_and_b32_e32 v75, 0xffff0000, v1
	v_lshlrev_b32_e32 v76, 16, v2
	v_and_b32_e32 v77, 0xffff0000, v2
	v_lshlrev_b32_e32 v78, 16, v3
	v_and_b32_e32 v79, 0xffff0000, v3
	ds_read_b128 v[4:7], v49 offset:1360
	ds_read_b128 v[8:11], v49 offset:1088
	ds_read_b128 v[12:15], v49 offset:816
	ds_read_b128 v[16:19], v49 offset:544
	ds_read_b128 v[20:23], v49 offset:272
	ds_read_b128 v[24:27], v49
	ds_read_b128 v[0:3], v49 offset:16
	v_pk_add_f32 v[28:29], v[28:29], v[72:73]
	s_waitcnt lgkmcnt(6)
	v_lshlrev_b32_e32 v36, 16, v4
	v_and_b32_e32 v37, 0xffff0000, v4
	v_pk_add_f32 v[28:29], v[28:29], v[36:37]
	s_waitcnt lgkmcnt(5)
	v_lshlrev_b32_e32 v36, 16, v8
	v_and_b32_e32 v37, 0xffff0000, v8
	v_pk_add_f32 v[28:29], v[28:29], v[36:37]
	s_waitcnt lgkmcnt(4)
	v_lshlrev_b32_e32 v36, 16, v12
	v_and_b32_e32 v37, 0xffff0000, v12
	v_pk_add_f32 v[28:29], v[28:29], v[36:37]
	s_waitcnt lgkmcnt(3)
	v_lshlrev_b32_e32 v36, 16, v16
	v_and_b32_e32 v37, 0xffff0000, v16
	v_pk_add_f32 v[28:29], v[28:29], v[36:37]
	s_waitcnt lgkmcnt(2)
	v_lshlrev_b32_e32 v36, 16, v20
	v_and_b32_e32 v37, 0xffff0000, v20
	v_pk_add_f32 v[28:29], v[28:29], v[36:37]
	s_waitcnt lgkmcnt(1)
	v_lshlrev_b32_e32 v36, 16, v24
	v_and_b32_e32 v37, 0xffff0000, v24
	v_pk_add_f32 v[28:29], v[28:29], v[36:37]
	v_lshlrev_b32_e32 v8, 16, v9
	v_pk_fma_f32 v[28:29], v[48:49], v[28:29], v[58:59] op_sel_hi:[0,1,1] neg_lo:[0,0,1] neg_hi:[0,0,1]
	v_cvt_pk_bf16_f32 v4, v28, v29
	v_pk_add_f32 v[28:29], v[30:31], v[38:39]
	v_lshlrev_b32_e32 v30, 16, v5
	v_pk_add_f32 v[28:29], v[28:29], v[46:47]
	v_and_b32_e32 v31, 0xffff0000, v5
	v_pk_add_f32 v[28:29], v[28:29], v[74:75]
	v_and_b32_e32 v9, 0xffff0000, v9
	v_pk_add_f32 v[28:29], v[28:29], v[30:31]
	v_lshlrev_b32_e32 v12, 16, v13
	v_pk_add_f32 v[8:9], v[28:29], v[8:9]
	v_and_b32_e32 v13, 0xffff0000, v13
	v_pk_add_f32 v[8:9], v[8:9], v[12:13]
	v_lshlrev_b32_e32 v12, 16, v17
	v_and_b32_e32 v13, 0xffff0000, v17
	v_pk_add_f32 v[8:9], v[8:9], v[12:13]
	v_lshlrev_b32_e32 v12, 16, v21
	v_and_b32_e32 v13, 0xffff0000, v21
	v_pk_add_f32 v[8:9], v[8:9], v[12:13]
	v_lshlrev_b32_e32 v12, 16, v25
	v_and_b32_e32 v13, 0xffff0000, v25
	v_pk_add_f32 v[8:9], v[8:9], v[12:13]
	v_lshlrev_b32_e32 v12, 16, v6
	v_pk_fma_f32 v[8:9], v[48:49], v[8:9], v[54:55] op_sel_hi:[0,1,1] neg_lo:[0,0,1] neg_hi:[0,0,1]
	v_cvt_pk_bf16_f32 v5, v8, v9
	v_pk_add_f32 v[8:9], v[32:33], v[40:41]
	v_and_b32_e32 v13, 0xffff0000, v6
	v_pk_add_f32 v[8:9], v[8:9], v[68:69]
	s_nop 0
	v_pk_add_f32 v[8:9], v[8:9], v[76:77]
	s_nop 0
	v_pk_add_f32 v[8:9], v[8:9], v[12:13]
	v_lshlrev_b32_e32 v12, 16, v10
	v_and_b32_e32 v13, 0xffff0000, v10
	v_pk_add_f32 v[8:9], v[8:9], v[12:13]
	v_lshlrev_b32_e32 v12, 16, v14
	v_and_b32_e32 v13, 0xffff0000, v14
	v_pk_add_f32 v[8:9], v[8:9], v[12:13]
	v_lshlrev_b32_e32 v12, 16, v18
	v_and_b32_e32 v13, 0xffff0000, v18
	v_pk_add_f32 v[8:9], v[8:9], v[12:13]
	v_lshlrev_b32_e32 v12, 16, v22
	v_and_b32_e32 v13, 0xffff0000, v22
	v_pk_add_f32 v[8:9], v[8:9], v[12:13]
	v_lshlrev_b32_e32 v12, 16, v26
	v_and_b32_e32 v13, 0xffff0000, v26
	v_pk_add_f32 v[8:9], v[8:9], v[12:13]
	v_lshlrev_b32_e32 v12, 16, v7
	v_pk_fma_f32 v[8:9], v[48:49], v[8:9], v[52:53] op_sel_hi:[0,1,1] neg_lo:[0,0,1] neg_hi:[0,0,1]
	v_cvt_pk_bf16_f32 v6, v8, v9
	v_pk_add_f32 v[8:9], v[34:35], v[42:43]
	v_and_b32_e32 v13, 0xffff0000, v7
	v_pk_add_f32 v[8:9], v[8:9], v[70:71]
	v_lshlrev_b32_e32 v10, 16, v11
	v_pk_add_f32 v[8:9], v[8:9], v[78:79]
	v_and_b32_e32 v11, 0xffff0000, v11
	v_pk_add_f32 v[8:9], v[8:9], v[12:13]
	s_nop 0
	v_pk_add_f32 v[8:9], v[8:9], v[10:11]
	v_lshlrev_b32_e32 v10, 16, v15
	v_and_b32_e32 v11, 0xffff0000, v15
	v_pk_add_f32 v[8:9], v[8:9], v[10:11]
	v_lshlrev_b32_e32 v10, 16, v19
	v_and_b32_e32 v11, 0xffff0000, v19
	v_pk_add_f32 v[8:9], v[8:9], v[10:11]
	v_lshlrev_b32_e32 v10, 16, v23
	v_and_b32_e32 v11, 0xffff0000, v23
	v_pk_add_f32 v[8:9], v[8:9], v[10:11]
	v_lshlrev_b32_e32 v10, 16, v27
	v_and_b32_e32 v11, 0xffff0000, v27
	v_pk_add_f32 v[8:9], v[8:9], v[10:11]
	s_nop 0
	v_pk_fma_f32 v[8:9], v[48:49], v[8:9], v[50:51] op_sel_hi:[0,1,1] neg_lo:[0,0,1] neg_hi:[0,0,1]
	v_cvt_pk_bf16_f32 v7, v8, v9
	ds_write_b128 v116, v[4:7]
	ds_read_b128 v[4:7], v49 offset:4096
	ds_read_b128 v[8:11], v49 offset:3824
	ds_read_b128 v[12:15], v49 offset:3552
	ds_read_b128 v[16:19], v49 offset:3280
	ds_read_b128 v[20:23], v49 offset:3008
	ds_read_b128 v[24:27], v49 offset:2736
	ds_read_b128 v[28:31], v49 offset:2464
	ds_read_b128 v[32:35], v49 offset:2192
	s_waitcnt lgkmcnt(7)
; #define LAS __attribute__((address_space(3)))
; __device__ __forceinline__ unsigned pk2(float lo, float hi) { f32x2_t v = {lo, hi}; bf16x2_t b = __builtin_convertvector(v, bf16x2_t); return __builtin_bit_cast(unsigned, b); }
; __device__ __forceinline__ float bflo(unsigned w) { return __uint_as_float(w << 16); }
; __device__ __forceinline__ float bfhi(unsigned w) { return __uint_as_float(w & 0xffff0000u); }
; template <int W> __device__ __forceinline__ void pool_fill(LAS unsigned char* Al, const LAS unsigned char* Ul, int tid, int tt0) {
;     ...
;     for (int ch = 0; ch < 4; ++ch) {
;         float acc[8];
; #pragma unroll
;         for (int e = 0; e < 8; ++e) acc[e] = 0.f;
;         v4u self = (v4u){0u, 0u, 0u, 0u};
; #pragma unroll
;         for (int j = 0; j < W; ++j) { const v4u x = *(const LAS v4u*)(Ul + (t + 15 - j) * RS + (cq * 32 + ch * 8) * 2); if (j == 0) self = x;
; #pragma unroll
;             for (int e = 0; e < 4; ++e) { acc[2 * e] += bflo(x[e]); acc[2 * e + 1] += bfhi(x[e]); } }
;         v4u o;
; #pragma unroll
;         for (int e = 0; e < 4; ++e) o[e] = pk2(acc[2 * e] * inv - bflo(self[e]), acc[2 * e + 1] * inv - bfhi(self[e]));
;         *(LAS v4u*)(Al + t * RS + (cq * 32 + ch * 8) * 2) = o;
	v_lshlrev_b32_e32 v100, 16, v4
	v_and_b32_e32 v101, 0xffff0000, v4
	s_waitcnt lgkmcnt(6)
	v_lshlrev_b32_e32 v102, 16, v8
	v_and_b32_e32 v103, 0xffff0000, v8
	s_waitcnt lgkmcnt(0)
	v_lshlrev_b32_e32 v72, 16, v32
	v_and_b32_e32 v73, 0xffff0000, v32
	v_lshlrev_b32_e32 v74, 16, v33
	v_and_b32_e32 v75, 0xffff0000, v33
	v_lshlrev_b32_e32 v76, 16, v34
	v_and_b32_e32 v77, 0xffff0000, v34
	v_lshlrev_b32_e32 v78, 16, v35
	v_and_b32_e32 v79, 0xffff0000, v35
	ds_read_b128 v[32:35], v49 offset:1920
	v_pk_add_f32 v[114:115], v[100:101], 0 op_sel_hi:[1,0]
	v_lshlrev_b32_e32 v104, 16, v12
	v_and_b32_e32 v105, 0xffff0000, v12
	v_pk_add_f32 v[102:103], v[114:115], v[102:103]
	v_lshlrev_b32_e32 v106, 16, v16
	v_and_b32_e32 v107, 0xffff0000, v16
	v_pk_add_f32 v[102:103], v[102:103], v[104:105]
	s_waitcnt lgkmcnt(0)
	v_lshlrev_b32_e32 v80, 16, v32
	v_and_b32_e32 v81, 0xffff0000, v32
	v_lshlrev_b32_e32 v82, 16, v33
	v_and_b32_e32 v83, 0xffff0000, v33
	v_lshlrev_b32_e32 v84, 16, v34
	v_and_b32_e32 v85, 0xffff0000, v34
	v_lshlrev_b32_e32 v86, 16, v35
	v_and_b32_e32 v87, 0xffff0000, v35
	ds_read_b128 v[32:35], v49 offset:1648
	v_lshlrev_b32_e32 v108, 16, v20
	v_and_b32_e32 v109, 0xffff0000, v20
	v_pk_add_f32 v[102:103], v[102:103], v[106:107]
	v_lshlrev_b32_e32 v110, 16, v24
	v_and_b32_e32 v111, 0xffff0000, v24
	v_pk_add_f32 v[102:103], v[102:103], v[108:109]
	v_lshlrev_b32_e32 v112, 16, v28
	v_and_b32_e32 v113, 0xffff0000, v28
	v_pk_add_f32 v[102:103], v[102:103], v[110:111]
	s_waitcnt lgkmcnt(0)
	v_lshlrev_b32_e32 v88, 16, v32
	v_pk_add_f32 v[102:103], v[102:103], v[112:113]
	v_and_b32_e32 v89, 0xffff0000, v32
	v_pk_add_f32 v[72:73], v[102:103], v[72:73]
	v_lshlrev_b32_e32 v90, 16, v33
	v_and_b32_e32 v91, 0xffff0000, v33
	v_lshlrev_b32_e32 v96, 16, v34
	v_and_b32_e32 v97, 0xffff0000, v34
	v_lshlrev_b32_e32 v98, 16, v35
	v_and_b32_e32 v99, 0xffff0000, v35
	ds_read_b128 v[32:35], v49 offset:1376
	ds_read_b128 v[36:39], v49 offset:1104
	ds_read_b128 v[40:43], v49 offset:832
	ds_read_b128 v[44:47], v49 offset:560
	ds_read_b128 v[68:71], v49 offset:288
	v_pk_add_f32 v[72:73], v[72:73], v[80:81]
	s_waitcnt lgkmcnt(4)
	v_lshlrev_b32_e32 v80, 16, v32
	v_pk_add_f32 v[72:73], v[72:73], v[88:89]
	v_and_b32_e32 v81, 0xffff0000, v32
	v_pk_add_f32 v[72:73], v[72:73], v[80:81]
	s_waitcnt lgkmcnt(3)
	v_lshlrev_b32_e32 v80, 16, v36
	v_and_b32_e32 v81, 0xffff0000, v36
	v_pk_add_f32 v[72:73], v[72:73], v[80:81]
	s_waitcnt lgkmcnt(2)
	v_lshlrev_b32_e32 v80, 16, v40
	v_and_b32_e32 v81, 0xffff0000, v40
	v_pk_add_f32 v[72:73], v[72:73], v[80:81]
	s_waitcnt lgkmcnt(1)
	v_lshlrev_b32_e32 v80, 16, v44
	v_and_b32_e32 v81, 0xffff0000, v44
	v_pk_add_f32 v[72:73], v[72:73], v[80:81]
	s_waitcnt lgkmcnt(0)
	v_lshlrev_b32_e32 v80, 16, v68
	v_and_b32_e32 v81, 0xffff0000, v68
	v_pk_add_f32 v[72:73], v[72:73], v[80:81]
	v_lshlrev_b32_e32 v80, 16, v0
	v_and_b32_e32 v81, 0xffff0000, v0
	v_pk_add_f32 v[72:73], v[72:73], v[80:81]
	v_lshlrev_b32_e32 v4, 16, v5
	v_pk_fma_f32 v[72:73], v[48:49], v[72:73], v[100:101] op_sel_hi:[0,1,1] neg_lo:[0,0,1] neg_hi:[0,0,1]
	v_and_b32_e32 v5, 0xffff0000, v5
	v_cvt_pk_bf16_f32 v0, v72, v73
	v_lshlrev_b32_e32 v8, 16, v9
	v_and_b32_e32 v9, 0xffff0000, v9
	v_pk_add_f32 v[72:73], v[4:5], 0 op_sel_hi:[1,0]
	v_lshlrev_b32_e32 v12, 16, v13
	v_and_b32_e32 v13, 0xffff0000, v13
	v_pk_add_f32 v[8:9], v[72:73], v[8:9]
	v_lshlrev_b32_e32 v16, 16, v17
	v_and_b32_e32 v17, 0xffff0000, v17
	v_pk_add_f32 v[8:9], v[8:9], v[12:13]
	v_lshlrev_b32_e32 v20, 16, v21
	v_and_b32_e32 v21, 0xffff0000, v21
	v_pk_add_f32 v[8:9], v[8:9], v[16:17]
	v_lshlrev_b32_e32 v24, 16, v25
	v_and_b32_e32 v25, 0xffff0000, v25
	v_pk_add_f32 v[8:9], v[8:9], v[20:21]
	v_lshlrev_b32_e32 v28, 16, v29
	v_and_b32_e32 v29, 0xffff0000, v29
	v_pk_add_f32 v[8:9], v[8:9], v[24:25]
	v_lshlrev_b32_e32 v12, 16, v33
	v_pk_add_f32 v[8:9], v[8:9], v[28:29]
	v_and_b32_e32 v13, 0xffff0000, v33
	v_pk_add_f32 v[8:9], v[8:9], v[74:75]
	v_lshlrev_b32_e32 v16, 16, v18
	v_pk_add_f32 v[8:9], v[8:9], v[82:83]
	v_and_b32_e32 v17, 0xffff0000, v18
	v_pk_add_f32 v[8:9], v[8:9], v[90:91]
	v_lshlrev_b32_e32 v20, 16, v22
	v_pk_add_f32 v[8:9], v[8:9], v[12:13]
	v_lshlrev_b32_e32 v12, 16, v37
	v_and_b32_e32 v13, 0xffff0000, v37
	v_pk_add_f32 v[8:9], v[8:9], v[12:13]
	v_lshlrev_b32_e32 v12, 16, v41
	v_and_b32_e32 v13, 0xffff0000, v41
	v_pk_add_f32 v[8:9], v[8:9], v[12:13]
	v_lshlrev_b32_e32 v12, 16, v45
	v_and_b32_e32 v13, 0xffff0000, v45
	v_pk_add_f32 v[8:9], v[8:9], v[12:13]
	v_lshlrev_b32_e32 v12, 16, v69
	v_and_b32_e32 v13, 0xffff0000, v69
	v_pk_add_f32 v[8:9], v[8:9], v[12:13]
	v_lshlrev_b32_e32 v12, 16, v1
	v_and_b32_e32 v13, 0xffff0000, v1
	v_pk_add_f32 v[8:9], v[8:9], v[12:13]
	v_lshlrev_b32_e32 v12, 16, v14
	v_pk_fma_f32 v[4:5], v[48:49], v[8:9], v[4:5] op_sel_hi:[0,1,1] neg_lo:[0,0,1] neg_hi:[0,0,1]
	v_cvt_pk_bf16_f32 v1, v4, v5
	v_lshlrev_b32_e32 v4, 16, v6
	v_and_b32_e32 v5, 0xffff0000, v6
	v_lshlrev_b32_e32 v8, 16, v10
	v_and_b32_e32 v9, 0xffff0000, v10
	v_pk_add_f32 v[32:33], v[4:5], 0 op_sel_hi:[1,0]
	v_and_b32_e32 v13, 0xffff0000, v14
	v_pk_add_f32 v[8:9], v[32:33], v[8:9]
	v_and_b32_e32 v21, 0xffff0000, v22
	v_pk_add_f32 v[8:9], v[8:9], v[12:13]
	v_lshlrev_b32_e32 v24, 16, v26
	v_pk_add_f32 v[8:9], v[8:9], v[16:17]
	v_and_b32_e32 v25, 0xffff0000, v26
	v_pk_add_f32 v[8:9], v[8:9], v[20:21]
	v_lshlrev_b32_e32 v28, 16, v30
	v_and_b32_e32 v29, 0xffff0000, v30
	v_pk_add_f32 v[8:9], v[8:9], v[24:25]
	v_lshlrev_b32_e32 v12, 16, v34
	v_pk_add_f32 v[8:9], v[8:9], v[28:29]
	v_and_b32_e32 v13, 0xffff0000, v34
	v_pk_add_f32 v[8:9], v[8:9], v[76:77]
	v_lshlrev_b32_e32 v6, 16, v11
	v_pk_add_f32 v[8:9], v[8:9], v[84:85]
	v_lshlrev_b32_e32 v10, 16, v19
; #define LAS __attribute__((address_space(3)))
; __device__ __forceinline__ unsigned pk2(float lo, float hi) { f32x2_t v = {lo, hi}; bf16x2_t b = __builtin_convertvector(v, bf16x2_t); return __builtin_bit_cast(unsigned, b); }
; __device__ __forceinline__ float bflo(unsigned w) { return __uint_as_float(w << 16); }
; __device__ __forceinline__ float bfhi(unsigned w) { return __uint_as_float(w & 0xffff0000u); }
; template <int W> __device__ __forceinline__ void pool_fill(LAS unsigned char* Al, const LAS unsigned char* Ul, int tid, int tt0) {
;     ...
;     for (int ch = 0; ch < 4; ++ch) {
;         float acc[8];
; #pragma unroll
;         for (int e = 0; e < 8; ++e) acc[e] = 0.f;
;         v4u self = (v4u){0u, 0u, 0u, 0u};
; #pragma unroll
;         for (int j = 0; j < W; ++j) { const v4u x = *(const LAS v4u*)(Ul + (t + 15 - j) * RS + (cq * 32 + ch * 8) * 2); if (j == 0) self = x;
; #pragma unroll
;             for (int e = 0; e < 4; ++e) { acc[2 * e] += bflo(x[e]); acc[2 * e + 1] += bfhi(x[e]); } }
;         v4u o;
; #pragma unroll
;         for (int e = 0; e < 4; ++e) o[e] = pk2(acc[2 * e] * inv - bflo(self[e]), acc[2 * e + 1] * inv - bfhi(self[e]));
;         *(LAS v4u*)(Al + t * RS + (cq * 32 + ch * 8) * 2) = o;
	v_pk_add_f32 v[8:9], v[8:9], v[96:97]
	v_lshlrev_b32_e32 v14, 16, v27
	v_pk_add_f32 v[8:9], v[8:9], v[12:13]
	v_lshlrev_b32_e32 v12, 16, v38
	v_and_b32_e32 v13, 0xffff0000, v38
	v_pk_add_f32 v[8:9], v[8:9], v[12:13]
	v_lshlrev_b32_e32 v12, 16, v42
	v_and_b32_e32 v13, 0xffff0000, v42
	v_pk_add_f32 v[8:9], v[8:9], v[12:13]
	v_lshlrev_b32_e32 v12, 16, v46
	v_and_b32_e32 v13, 0xffff0000, v46
	v_pk_add_f32 v[8:9], v[8:9], v[12:13]
	v_lshlrev_b32_e32 v12, 16, v70
	v_and_b32_e32 v13, 0xffff0000, v70
	v_pk_add_f32 v[8:9], v[8:9], v[12:13]
	v_lshlrev_b32_e32 v12, 16, v2
	v_and_b32_e32 v13, 0xffff0000, v2
	v_pk_add_f32 v[8:9], v[8:9], v[12:13]
	v_lshlrev_b32_e32 v12, 16, v23
	v_pk_fma_f32 v[4:5], v[48:49], v[8:9], v[4:5] op_sel_hi:[0,1,1] neg_lo:[0,0,1] neg_hi:[0,0,1]
	v_cvt_pk_bf16_f32 v2, v4, v5
	v_lshlrev_b32_e32 v4, 16, v7
	v_and_b32_e32 v5, 0xffff0000, v7
	v_and_b32_e32 v7, 0xffff0000, v11
	v_and_b32_e32 v11, 0xffff0000, v19
	v_pk_add_f32 v[18:19], v[4:5], 0 op_sel_hi:[1,0]
	v_lshlrev_b32_e32 v8, 16, v15
	v_and_b32_e32 v9, 0xffff0000, v15
	v_pk_add_f32 v[6:7], v[18:19], v[6:7]
	v_and_b32_e32 v13, 0xffff0000, v23
	v_pk_add_f32 v[6:7], v[6:7], v[8:9]
	v_and_b32_e32 v15, 0xffff0000, v27
	v_pk_add_f32 v[6:7], v[6:7], v[10:11]
	v_lshlrev_b32_e32 v16, 16, v31
	v_pk_add_f32 v[6:7], v[6:7], v[12:13]
	v_and_b32_e32 v17, 0xffff0000, v31
	v_pk_add_f32 v[6:7], v[6:7], v[14:15]
	v_lshlrev_b32_e32 v8, 16, v35
	v_pk_add_f32 v[6:7], v[6:7], v[16:17]
	v_and_b32_e32 v9, 0xffff0000, v35
	v_pk_add_f32 v[6:7], v[6:7], v[78:79]
	s_nop 0
	v_pk_add_f32 v[6:7], v[6:7], v[86:87]
	s_nop 0
	v_pk_add_f32 v[6:7], v[6:7], v[98:99]
	s_nop 0
	v_pk_add_f32 v[6:7], v[6:7], v[8:9]
	v_lshlrev_b32_e32 v8, 16, v39
	v_and_b32_e32 v9, 0xffff0000, v39
	v_pk_add_f32 v[6:7], v[6:7], v[8:9]
	v_lshlrev_b32_e32 v8, 16, v43
	v_and_b32_e32 v9, 0xffff0000, v43
	v_pk_add_f32 v[6:7], v[6:7], v[8:9]
	v_lshlrev_b32_e32 v8, 16, v47
	v_and_b32_e32 v9, 0xffff0000, v47
	v_pk_add_f32 v[6:7], v[6:7], v[8:9]
	v_lshlrev_b32_e32 v8, 16, v71
	v_and_b32_e32 v9, 0xffff0000, v71
	v_pk_add_f32 v[6:7], v[6:7], v[8:9]
	v_lshlrev_b32_e32 v8, 16, v3
	v_and_b32_e32 v9, 0xffff0000, v3
	v_pk_add_f32 v[6:7], v[6:7], v[8:9]
	s_nop 0
	v_pk_fma_f32 v[4:5], v[48:49], v[6:7], v[4:5] op_sel_hi:[0,1,1] neg_lo:[0,0,1] neg_hi:[0,0,1]
	v_cvt_pk_bf16_f32 v3, v4, v5
	ds_write_b128 v116, v[0:3] offset:16
	ds_read_b128 v[0:3], v49 offset:4112
	ds_read_b128 v[4:7], v49 offset:3840
	ds_read_b128 v[8:11], v49 offset:3568
	ds_read_b128 v[12:15], v49 offset:3296
	ds_read_b128 v[16:19], v49 offset:3024
	ds_read_b128 v[20:23], v49 offset:2752
	ds_read_b128 v[24:27], v49 offset:2480
	ds_read_b128 v[28:31], v49 offset:2208
	s_waitcnt lgkmcnt(7)
	v_lshlrev_b32_e32 v100, 16, v0
	v_and_b32_e32 v101, 0xffff0000, v0
	s_waitcnt lgkmcnt(6)
	v_lshlrev_b32_e32 v102, 16, v4
	v_and_b32_e32 v103, 0xffff0000, v4
	s_waitcnt lgkmcnt(0)
	v_lshlrev_b32_e32 v72, 16, v28
	v_and_b32_e32 v73, 0xffff0000, v28
	v_lshlrev_b32_e32 v74, 16, v29
	v_and_b32_e32 v75, 0xffff0000, v29
	v_lshlrev_b32_e32 v76, 16, v30
	v_and_b32_e32 v77, 0xffff0000, v30
	v_lshlrev_b32_e32 v78, 16, v31
	v_and_b32_e32 v79, 0xffff0000, v31
	ds_read_b128 v[28:31], v49 offset:1936
	v_pk_add_f32 v[114:115], v[100:101], 0 op_sel_hi:[1,0]
	v_lshlrev_b32_e32 v104, 16, v8
	v_and_b32_e32 v105, 0xffff0000, v8
	v_pk_add_f32 v[102:103], v[114:115], v[102:103]
	v_lshlrev_b32_e32 v106, 16, v12
	v_and_b32_e32 v107, 0xffff0000, v12
	v_pk_add_f32 v[102:103], v[102:103], v[104:105]
	s_waitcnt lgkmcnt(0)
	v_lshlrev_b32_e32 v80, 16, v28
	v_and_b32_e32 v81, 0xffff0000, v28
	v_lshlrev_b32_e32 v82, 16, v29
	v_and_b32_e32 v83, 0xffff0000, v29
	v_lshlrev_b32_e32 v84, 16, v30
	v_and_b32_e32 v85, 0xffff0000, v30
	v_lshlrev_b32_e32 v86, 16, v31
	v_and_b32_e32 v87, 0xffff0000, v31
	ds_read_b128 v[28:31], v49 offset:1664
	v_lshlrev_b32_e32 v108, 16, v16
	v_and_b32_e32 v109, 0xffff0000, v16
	v_pk_add_f32 v[102:103], v[102:103], v[106:107]
	v_lshlrev_b32_e32 v110, 16, v20
	v_and_b32_e32 v111, 0xffff0000, v20
	v_pk_add_f32 v[102:103], v[102:103], v[108:109]
	v_lshlrev_b32_e32 v112, 16, v24
	v_and_b32_e32 v113, 0xffff0000, v24
	v_pk_add_f32 v[102:103], v[102:103], v[110:111]
	s_waitcnt lgkmcnt(0)
	v_lshlrev_b32_e32 v88, 16, v28
	v_pk_add_f32 v[102:103], v[102:103], v[112:113]
	v_and_b32_e32 v89, 0xffff0000, v28
	v_pk_add_f32 v[72:73], v[102:103], v[72:73]
	v_lshlrev_b32_e32 v90, 16, v29
	v_pk_add_f32 v[72:73], v[72:73], v[80:81]
	v_and_b32_e32 v91, 0xffff0000, v29
	v_lshlrev_b32_e32 v96, 16, v30
	v_and_b32_e32 v97, 0xffff0000, v30
	v_lshlrev_b32_e32 v98, 16, v31
	v_and_b32_e32 v99, 0xffff0000, v31
	ds_read_b128 v[28:31], v49 offset:1392
	ds_read_b128 v[32:35], v49 offset:1120
	ds_read_b128 v[36:39], v49 offset:848
	ds_read_b128 v[40:43], v49 offset:576
	ds_read_b128 v[44:47], v49 offset:304
	ds_read_b128 v[68:71], v49 offset:32
	v_pk_add_f32 v[72:73], v[72:73], v[88:89]
	s_waitcnt lgkmcnt(5)
	v_lshlrev_b32_e32 v80, 16, v28
	v_and_b32_e32 v81, 0xffff0000, v28
	v_pk_add_f32 v[72:73], v[72:73], v[80:81]
	s_waitcnt lgkmcnt(4)
	v_lshlrev_b32_e32 v80, 16, v32
	v_and_b32_e32 v81, 0xffff0000, v32
	v_pk_add_f32 v[72:73], v[72:73], v[80:81]
	s_waitcnt lgkmcnt(3)
	v_lshlrev_b32_e32 v80, 16, v36
	v_and_b32_e32 v81, 0xffff0000, v36
	v_pk_add_f32 v[72:73], v[72:73], v[80:81]
	s_waitcnt lgkmcnt(2)
	v_lshlrev_b32_e32 v80, 16, v40
	v_and_b32_e32 v81, 0xffff0000, v40
	v_pk_add_f32 v[72:73], v[72:73], v[80:81]
	s_waitcnt lgkmcnt(1)
	v_lshlrev_b32_e32 v80, 16, v44
	v_and_b32_e32 v81, 0xffff0000, v44
	v_pk_add_f32 v[72:73], v[72:73], v[80:81]
	s_waitcnt lgkmcnt(0)
; #define LAS __attribute__((address_space(3)))
; __device__ __forceinline__ unsigned pk2(float lo, float hi) { f32x2_t v = {lo, hi}; bf16x2_t b = __builtin_convertvector(v, bf16x2_t); return __builtin_bit_cast(unsigned, b); }
; __device__ __forceinline__ float bflo(unsigned w) { return __uint_as_float(w << 16); }
; __device__ __forceinline__ float bfhi(unsigned w) { return __uint_as_float(w & 0xffff0000u); }
; template <int W> __device__ __forceinline__ void pool_fill(LAS unsigned char* Al, const LAS unsigned char* Ul, int tid, int tt0) {
;     ...
;     for (int ch = 0; ch < 4; ++ch) {
;         float acc[8];
; #pragma unroll
;         for (int e = 0; e < 8; ++e) acc[e] = 0.f;
;         v4u self = (v4u){0u, 0u, 0u, 0u};
; #pragma unroll
;         for (int j = 0; j < W; ++j) { const v4u x = *(const LAS v4u*)(Ul + (t + 15 - j) * RS + (cq * 32 + ch * 8) * 2); if (j == 0) self = x;
; #pragma unroll
;             for (int e = 0; e < 4; ++e) { acc[2 * e] += bflo(x[e]); acc[2 * e + 1] += bfhi(x[e]); } }
;         v4u o;
; #pragma unroll
;         for (int e = 0; e < 4; ++e) o[e] = pk2(acc[2 * e] * inv - bflo(self[e]), acc[2 * e + 1] * inv - bfhi(self[e]));
;         *(LAS v4u*)(Al + t * RS + (cq * 32 + ch * 8) * 2) = o;
	v_lshlrev_b32_e32 v80, 16, v68
	v_and_b32_e32 v81, 0xffff0000, v68
	v_pk_add_f32 v[72:73], v[72:73], v[80:81]
	v_lshlrev_b32_e32 v4, 16, v5
	v_pk_fma_f32 v[72:73], v[48:49], v[72:73], v[100:101] op_sel_hi:[0,1,1] neg_lo:[0,0,1] neg_hi:[0,0,1]
	v_cvt_pk_bf16_f32 v0, v72, v73
	v_lshlrev_b32_e32 v72, 16, v1
	v_and_b32_e32 v73, 0xffff0000, v1
	v_and_b32_e32 v5, 0xffff0000, v5
	v_pk_add_f32 v[80:81], v[72:73], 0 op_sel_hi:[1,0]
	v_lshlrev_b32_e32 v8, 16, v9
	v_and_b32_e32 v9, 0xffff0000, v9
	v_pk_add_f32 v[4:5], v[80:81], v[4:5]
	v_lshlrev_b32_e32 v12, 16, v13
	v_and_b32_e32 v13, 0xffff0000, v13
	v_pk_add_f32 v[4:5], v[4:5], v[8:9]
	v_lshlrev_b32_e32 v16, 16, v17
	v_and_b32_e32 v17, 0xffff0000, v17
	v_pk_add_f32 v[4:5], v[4:5], v[12:13]
	v_lshlrev_b32_e32 v20, 16, v21
	v_and_b32_e32 v21, 0xffff0000, v21
	v_pk_add_f32 v[4:5], v[4:5], v[16:17]
	v_lshlrev_b32_e32 v24, 16, v25
	v_and_b32_e32 v25, 0xffff0000, v25
	v_pk_add_f32 v[4:5], v[4:5], v[20:21]
	v_lshlrev_b32_e32 v8, 16, v29
	v_pk_add_f32 v[4:5], v[4:5], v[24:25]
	v_and_b32_e32 v9, 0xffff0000, v29
	v_pk_add_f32 v[4:5], v[4:5], v[74:75]
	v_lshlrev_b32_e32 v12, 16, v10
	v_pk_add_f32 v[4:5], v[4:5], v[82:83]
	v_and_b32_e32 v13, 0xffff0000, v10
	v_pk_add_f32 v[4:5], v[4:5], v[90:91]
	v_lshlrev_b32_e32 v16, 16, v14
	v_pk_add_f32 v[4:5], v[4:5], v[8:9]
	v_lshlrev_b32_e32 v8, 16, v33
	v_and_b32_e32 v9, 0xffff0000, v33
	v_pk_add_f32 v[4:5], v[4:5], v[8:9]
	v_lshlrev_b32_e32 v8, 16, v37
	v_and_b32_e32 v9, 0xffff0000, v37
	v_pk_add_f32 v[4:5], v[4:5], v[8:9]
	v_lshlrev_b32_e32 v8, 16, v41
	v_and_b32_e32 v9, 0xffff0000, v41
	v_pk_add_f32 v[4:5], v[4:5], v[8:9]
	v_lshlrev_b32_e32 v8, 16, v45
	v_and_b32_e32 v9, 0xffff0000, v45
	v_pk_add_f32 v[4:5], v[4:5], v[8:9]
	v_lshlrev_b32_e32 v8, 16, v69
	v_and_b32_e32 v9, 0xffff0000, v69
	v_pk_add_f32 v[4:5], v[4:5], v[8:9]
	v_lshlrev_b32_e32 v8, 16, v6
	v_pk_fma_f32 v[4:5], v[48:49], v[4:5], v[72:73] op_sel_hi:[0,1,1] neg_lo:[0,0,1] neg_hi:[0,0,1]
	v_cvt_pk_bf16_f32 v1, v4, v5
	v_lshlrev_b32_e32 v4, 16, v2
	v_and_b32_e32 v5, 0xffff0000, v2
	v_and_b32_e32 v9, 0xffff0000, v6
	v_pk_add_f32 v[32:33], v[4:5], 0 op_sel_hi:[1,0]
	v_and_b32_e32 v17, 0xffff0000, v14
	v_pk_add_f32 v[8:9], v[32:33], v[8:9]
	v_lshlrev_b32_e32 v20, 16, v18
	v_pk_add_f32 v[8:9], v[8:9], v[12:13]
	v_and_b32_e32 v21, 0xffff0000, v18
	v_pk_add_f32 v[8:9], v[8:9], v[16:17]
	v_lshlrev_b32_e32 v24, 16, v22
	v_and_b32_e32 v25, 0xffff0000, v22
	v_pk_add_f32 v[8:9], v[8:9], v[20:21]
	v_lshlrev_b32_e32 v28, 16, v26
	v_and_b32_e32 v29, 0xffff0000, v26
	v_pk_add_f32 v[8:9], v[8:9], v[24:25]
	v_lshlrev_b32_e32 v12, 16, v30
	v_pk_add_f32 v[8:9], v[8:9], v[28:29]
	v_and_b32_e32 v13, 0xffff0000, v30
	v_pk_add_f32 v[8:9], v[8:9], v[76:77]
	v_lshlrev_b32_e32 v6, 16, v7
	v_pk_add_f32 v[8:9], v[8:9], v[84:85]
	v_and_b32_e32 v7, 0xffff0000, v7
	v_pk_add_f32 v[8:9], v[8:9], v[96:97]
	v_lshlrev_b32_e32 v10, 16, v15
	v_pk_add_f32 v[8:9], v[8:9], v[12:13]
	v_lshlrev_b32_e32 v12, 16, v34
	v_and_b32_e32 v13, 0xffff0000, v34
	v_pk_add_f32 v[8:9], v[8:9], v[12:13]
	v_lshlrev_b32_e32 v12, 16, v38
	v_and_b32_e32 v13, 0xffff0000, v38
	v_pk_add_f32 v[8:9], v[8:9], v[12:13]
	v_lshlrev_b32_e32 v12, 16, v42
	v_and_b32_e32 v13, 0xffff0000, v42
	v_pk_add_f32 v[8:9], v[8:9], v[12:13]
	v_lshlrev_b32_e32 v12, 16, v46
	v_and_b32_e32 v13, 0xffff0000, v46
	v_pk_add_f32 v[8:9], v[8:9], v[12:13]
	v_lshlrev_b32_e32 v12, 16, v70
	v_and_b32_e32 v13, 0xffff0000, v70
	v_pk_add_f32 v[8:9], v[8:9], v[12:13]
	v_lshlrev_b32_e32 v12, 16, v19
	v_pk_fma_f32 v[4:5], v[48:49], v[8:9], v[4:5] op_sel_hi:[0,1,1] neg_lo:[0,0,1] neg_hi:[0,0,1]
	v_cvt_pk_bf16_f32 v2, v4, v5
	v_lshlrev_b32_e32 v4, 16, v3
	v_and_b32_e32 v5, 0xffff0000, v3
	v_and_b32_e32 v13, 0xffff0000, v19
	v_pk_add_f32 v[18:19], v[4:5], 0 op_sel_hi:[1,0]
	v_lshlrev_b32_e32 v8, 16, v11
	v_and_b32_e32 v9, 0xffff0000, v11
	v_pk_add_f32 v[6:7], v[18:19], v[6:7]
	v_and_b32_e32 v11, 0xffff0000, v15
	v_pk_add_f32 v[6:7], v[6:7], v[8:9]
	v_lshlrev_b32_e32 v14, 16, v23
	v_pk_add_f32 v[6:7], v[6:7], v[10:11]
	v_and_b32_e32 v15, 0xffff0000, v23
	v_pk_add_f32 v[6:7], v[6:7], v[12:13]
	v_lshlrev_b32_e32 v16, 16, v27
	v_and_b32_e32 v17, 0xffff0000, v27
	v_pk_add_f32 v[6:7], v[6:7], v[14:15]
	v_lshlrev_b32_e32 v8, 16, v31
	v_pk_add_f32 v[6:7], v[6:7], v[16:17]
	v_and_b32_e32 v9, 0xffff0000, v31
	v_pk_add_f32 v[6:7], v[6:7], v[78:79]
	s_nop 0
	v_pk_add_f32 v[6:7], v[6:7], v[86:87]
	s_nop 0
	v_pk_add_f32 v[6:7], v[6:7], v[98:99]
	s_nop 0
	v_pk_add_f32 v[6:7], v[6:7], v[8:9]
	v_lshlrev_b32_e32 v8, 16, v35
	v_and_b32_e32 v9, 0xffff0000, v35
	v_pk_add_f32 v[6:7], v[6:7], v[8:9]
	v_lshlrev_b32_e32 v8, 16, v39
	v_and_b32_e32 v9, 0xffff0000, v39
	v_pk_add_f32 v[6:7], v[6:7], v[8:9]
	v_lshlrev_b32_e32 v8, 16, v43
	v_and_b32_e32 v9, 0xffff0000, v43
	v_pk_add_f32 v[6:7], v[6:7], v[8:9]
	v_lshlrev_b32_e32 v8, 16, v47
	v_and_b32_e32 v9, 0xffff0000, v47
	v_pk_add_f32 v[6:7], v[6:7], v[8:9]
	v_lshlrev_b32_e32 v8, 16, v71
	v_and_b32_e32 v9, 0xffff0000, v71
	v_pk_add_f32 v[6:7], v[6:7], v[8:9]
	s_nop 0
	v_pk_fma_f32 v[4:5], v[48:49], v[6:7], v[4:5] op_sel_hi:[0,1,1] neg_lo:[0,0,1] neg_hi:[0,0,1]
	v_cvt_pk_bf16_f32 v3, v4, v5
	ds_write_b128 v116, v[0:3] offset:32
	ds_read_b128 v[0:3], v49 offset:4128
	s_waitcnt lgkmcnt(0)
	v_lshlrev_b32_e32 v44, 16, v0
	v_and_b32_e32 v45, 0xffff0000, v0
	v_lshlrev_b32_e32 v46, 16, v1
	v_and_b32_e32 v47, 0xffff0000, v1
	v_lshlrev_b32_e32 v32, 16, v2
	v_and_b32_e32 v33, 0xffff0000, v2
	v_lshlrev_b32_e32 v36, 16, v3
	v_and_b32_e32 v37, 0xffff0000, v3
	ds_read_b128 v[4:7], v49 offset:3856
	ds_read_b128 v[0:3], v49 offset:3584
	ds_read_b128 v[8:11], v49 offset:3312
	v_pk_add_f32 v[12:13], v[44:45], 0 op_sel_hi:[1,0]
	s_waitcnt lgkmcnt(2)
; #define LAS __attribute__((address_space(3)))
; __device__ __forceinline__ unsigned pk2(float lo, float hi) { f32x2_t v = {lo, hi}; bf16x2_t b = __builtin_convertvector(v, bf16x2_t); return __builtin_bit_cast(unsigned, b); }
; __device__ __forceinline__ float bflo(unsigned w) { return __uint_as_float(w << 16); }
; __device__ __forceinline__ float bfhi(unsigned w) { return __uint_as_float(w & 0xffff0000u); }
; template <int W> __device__ __forceinline__ void pool_fill(LAS unsigned char* Al, const LAS unsigned char* Ul, int tid, int tt0) {
;     ...
;     for (int ch = 0; ch < 4; ++ch) {
;         float acc[8];
; #pragma unroll
;         for (int e = 0; e < 8; ++e) acc[e] = 0.f;
;         v4u self = (v4u){0u, 0u, 0u, 0u};
; #pragma unroll
;         for (int j = 0; j < W; ++j) { const v4u x = *(const LAS v4u*)(Ul + (t + 15 - j) * RS + (cq * 32 + ch * 8) * 2); if (j == 0) self = x;
; #pragma unroll
;             for (int e = 0; e < 4; ++e) { acc[2 * e] += bflo(x[e]); acc[2 * e + 1] += bfhi(x[e]); } }
;         v4u o;
; #pragma unroll
;         for (int e = 0; e < 4; ++e) o[e] = pk2(acc[2 * e] * inv - bflo(self[e]), acc[2 * e + 1] * inv - bfhi(self[e]));
;         *(LAS v4u*)(Al + t * RS + (cq * 32 + ch * 8) * 2) = o;
	v_lshlrev_b32_e32 v14, 16, v4
	v_and_b32_e32 v15, 0xffff0000, v4
	v_pk_add_f32 v[12:13], v[12:13], v[14:15]
	s_waitcnt lgkmcnt(1)
	v_lshlrev_b32_e32 v14, 16, v0
	v_and_b32_e32 v15, 0xffff0000, v0
	v_pk_add_f32 v[12:13], v[12:13], v[14:15]
	s_waitcnt lgkmcnt(0)
	v_lshlrev_b32_e32 v14, 16, v8
	v_and_b32_e32 v15, 0xffff0000, v8
	v_pk_add_f32 v[42:43], v[12:13], v[14:15]
	v_pk_add_f32 v[12:13], v[46:47], 0 op_sel_hi:[1,0]
	v_lshlrev_b32_e32 v4, 16, v5
	v_and_b32_e32 v5, 0xffff0000, v5
	v_pk_add_f32 v[4:5], v[12:13], v[4:5]
	v_lshlrev_b32_e32 v0, 16, v1
	v_and_b32_e32 v1, 0xffff0000, v1
	v_pk_add_f32 v[0:1], v[4:5], v[0:1]
	v_lshlrev_b32_e32 v4, 16, v9
	v_and_b32_e32 v5, 0xffff0000, v9
	v_pk_add_f32 v[40:41], v[0:1], v[4:5]
	v_pk_add_f32 v[0:1], v[32:33], 0 op_sel_hi:[1,0]
	v_lshlrev_b32_e32 v4, 16, v6
	v_and_b32_e32 v5, 0xffff0000, v6
	v_pk_add_f32 v[0:1], v[0:1], v[4:5]
	v_lshlrev_b32_e32 v4, 16, v2
	v_and_b32_e32 v5, 0xffff0000, v2
	v_pk_add_f32 v[0:1], v[0:1], v[4:5]
	v_lshlrev_b32_e32 v4, 16, v10
	v_and_b32_e32 v5, 0xffff0000, v10
	v_pk_add_f32 v[38:39], v[0:1], v[4:5]
	v_pk_add_f32 v[0:1], v[36:37], 0 op_sel_hi:[1,0]
	v_lshlrev_b32_e32 v4, 16, v7
	v_and_b32_e32 v5, 0xffff0000, v7
	v_pk_add_f32 v[0:1], v[0:1], v[4:5]
	v_lshlrev_b32_e32 v2, 16, v3
	v_and_b32_e32 v3, 0xffff0000, v3
	v_pk_add_f32 v[0:1], v[0:1], v[2:3]
	v_lshlrev_b32_e32 v2, 16, v11
	v_and_b32_e32 v3, 0xffff0000, v11
	v_pk_add_f32 v[34:35], v[0:1], v[2:3]
	ds_read_b128 v[0:3], v49 offset:3040
	s_waitcnt lgkmcnt(0)
	v_lshlrev_b32_e32 v84, 16, v0
	v_and_b32_e32 v85, 0xffff0000, v0
	v_lshlrev_b32_e32 v78, 16, v1
	v_and_b32_e32 v79, 0xffff0000, v1
	v_lshlrev_b32_e32 v72, 16, v2
	v_and_b32_e32 v73, 0xffff0000, v2
	v_lshlrev_b32_e32 v68, 16, v3
	v_and_b32_e32 v69, 0xffff0000, v3
	ds_read_b128 v[0:3], v49 offset:2768
	v_pk_add_f32 v[42:43], v[42:43], v[84:85]
	v_pk_add_f32 v[40:41], v[40:41], v[78:79]
	s_waitcnt lgkmcnt(0)
	v_lshlrev_b32_e32 v88, 16, v0
	v_and_b32_e32 v89, 0xffff0000, v0
	v_lshlrev_b32_e32 v82, 16, v1
	v_and_b32_e32 v83, 0xffff0000, v1
	v_lshlrev_b32_e32 v76, 16, v2
	v_and_b32_e32 v77, 0xffff0000, v2
	v_lshlrev_b32_e32 v70, 16, v3
	v_and_b32_e32 v71, 0xffff0000, v3
	ds_read_b128 v[0:3], v49 offset:2496
	v_pk_add_f32 v[42:43], v[42:43], v[88:89]
	v_pk_add_f32 v[40:41], v[40:41], v[82:83]
	s_waitcnt lgkmcnt(0)
	v_lshlrev_b32_e32 v90, 16, v0
	v_and_b32_e32 v91, 0xffff0000, v0
	v_lshlrev_b32_e32 v86, 16, v1
	v_and_b32_e32 v87, 0xffff0000, v1
	v_lshlrev_b32_e32 v80, 16, v2
	v_and_b32_e32 v81, 0xffff0000, v2
	v_lshlrev_b32_e32 v74, 16, v3
	v_and_b32_e32 v75, 0xffff0000, v3
	ds_read_b128 v[0:3], v49 offset:2224
	ds_read_b128 v[4:7], v49 offset:1952
	ds_read_b128 v[8:11], v49 offset:1680
	ds_read_b128 v[12:15], v49 offset:1408
	ds_read_b128 v[16:19], v49 offset:1136
	ds_read_b128 v[20:23], v49 offset:864
	ds_read_b128 v[24:27], v49 offset:592
	ds_read_b128 v[28:31], v49 offset:320
	v_pk_add_f32 v[42:43], v[42:43], v[90:91]
	s_waitcnt lgkmcnt(7)
	v_lshlrev_b32_e32 v84, 16, v0
	v_and_b32_e32 v85, 0xffff0000, v0
	v_pk_add_f32 v[40:41], v[40:41], v[86:87]
	v_lshlrev_b32_e32 v0, 16, v1
	v_and_b32_e32 v1, 0xffff0000, v1
	v_pk_add_f32 v[42:43], v[42:43], v[84:85]
	s_waitcnt lgkmcnt(6)
	v_lshlrev_b32_e32 v84, 16, v4
	v_and_b32_e32 v85, 0xffff0000, v4
	v_pk_add_f32 v[0:1], v[40:41], v[0:1]
	v_lshlrev_b32_e32 v4, 16, v5
	v_and_b32_e32 v5, 0xffff0000, v5
	v_pk_add_f32 v[0:1], v[0:1], v[4:5]
	s_waitcnt lgkmcnt(5)
	v_lshlrev_b32_e32 v4, 16, v9
	v_and_b32_e32 v5, 0xffff0000, v9
	v_pk_add_f32 v[0:1], v[0:1], v[4:5]
	s_waitcnt lgkmcnt(4)
	v_lshlrev_b32_e32 v4, 16, v13
	v_and_b32_e32 v5, 0xffff0000, v13
	v_pk_add_f32 v[0:1], v[0:1], v[4:5]
	s_waitcnt lgkmcnt(3)
	v_lshlrev_b32_e32 v4, 16, v17
	v_and_b32_e32 v5, 0xffff0000, v17
	v_pk_add_f32 v[0:1], v[0:1], v[4:5]
	s_waitcnt lgkmcnt(2)
	v_lshlrev_b32_e32 v4, 16, v21
	v_and_b32_e32 v5, 0xffff0000, v21
	v_pk_add_f32 v[0:1], v[0:1], v[4:5]
	s_waitcnt lgkmcnt(1)
	v_lshlrev_b32_e32 v4, 16, v25
	v_and_b32_e32 v5, 0xffff0000, v25
	v_pk_add_f32 v[0:1], v[0:1], v[4:5]
	s_waitcnt lgkmcnt(0)
	v_lshlrev_b32_e32 v4, 16, v29
	v_and_b32_e32 v5, 0xffff0000, v29
	v_pk_add_f32 v[0:1], v[0:1], v[4:5]
	v_pk_add_f32 v[4:5], v[38:39], v[72:73]
	v_pk_add_f32 v[42:43], v[42:43], v[84:85]
	v_pk_add_f32 v[4:5], v[4:5], v[76:77]
	v_lshlrev_b32_e32 v84, 16, v8
	v_and_b32_e32 v85, 0xffff0000, v8
	v_pk_add_f32 v[4:5], v[4:5], v[80:81]
	v_lshlrev_b32_e32 v8, 16, v2
	v_and_b32_e32 v9, 0xffff0000, v2
	v_pk_add_f32 v[4:5], v[4:5], v[8:9]
	v_lshlrev_b32_e32 v8, 16, v6
	v_and_b32_e32 v9, 0xffff0000, v6
	v_pk_add_f32 v[4:5], v[4:5], v[8:9]
	v_lshlrev_b32_e32 v8, 16, v10
	v_and_b32_e32 v9, 0xffff0000, v10
	v_pk_add_f32 v[4:5], v[4:5], v[8:9]
	v_lshlrev_b32_e32 v8, 16, v14
	v_and_b32_e32 v9, 0xffff0000, v14
	v_pk_add_f32 v[4:5], v[4:5], v[8:9]
	v_lshlrev_b32_e32 v8, 16, v18
	v_and_b32_e32 v9, 0xffff0000, v18
	v_pk_add_f32 v[4:5], v[4:5], v[8:9]
	v_lshlrev_b32_e32 v8, 16, v22
	v_and_b32_e32 v9, 0xffff0000, v22
	v_pk_add_f32 v[4:5], v[4:5], v[8:9]
	v_lshlrev_b32_e32 v8, 16, v26
	v_and_b32_e32 v9, 0xffff0000, v26
	v_pk_add_f32 v[4:5], v[4:5], v[8:9]
	v_lshlrev_b32_e32 v8, 16, v30
	v_and_b32_e32 v9, 0xffff0000, v30
	v_pk_add_f32 v[4:5], v[4:5], v[8:9]
	v_pk_add_f32 v[8:9], v[34:35], v[68:69]
	v_lshlrev_b32_e32 v2, 16, v3
	v_pk_add_f32 v[8:9], v[8:9], v[70:71]
	v_and_b32_e32 v3, 0xffff0000, v3
	v_pk_add_f32 v[8:9], v[8:9], v[74:75]
	v_lshlrev_b32_e32 v6, 16, v7
	v_pk_add_f32 v[2:3], v[8:9], v[2:3]
	v_and_b32_e32 v7, 0xffff0000, v7
	v_pk_add_f32 v[2:3], v[2:3], v[6:7]
	v_lshlrev_b32_e32 v6, 16, v11
	v_and_b32_e32 v7, 0xffff0000, v11
	v_pk_add_f32 v[42:43], v[42:43], v[84:85]
	v_lshlrev_b32_e32 v84, 16, v12
	v_and_b32_e32 v85, 0xffff0000, v12
	v_pk_add_f32 v[2:3], v[2:3], v[6:7]
	v_lshlrev_b32_e32 v6, 16, v15
	v_and_b32_e32 v7, 0xffff0000, v15
	v_pk_add_f32 v[42:43], v[42:43], v[84:85]
	v_lshlrev_b32_e32 v84, 16, v16
	v_and_b32_e32 v85, 0xffff0000, v16
	v_pk_add_f32 v[2:3], v[2:3], v[6:7]
	v_lshlrev_b32_e32 v6, 16, v19
	v_and_b32_e32 v7, 0xffff0000, v19
	v_pk_add_f32 v[42:43], v[42:43], v[84:85]
	v_lshlrev_b32_e32 v84, 16, v20
	v_and_b32_e32 v85, 0xffff0000, v20
	v_pk_add_f32 v[2:3], v[2:3], v[6:7]
	v_lshlrev_b32_e32 v6, 16, v23
	v_and_b32_e32 v7, 0xffff0000, v23
	v_pk_add_f32 v[42:43], v[42:43], v[84:85]
	v_lshlrev_b32_e32 v84, 16, v24
	v_and_b32_e32 v85, 0xffff0000, v24
	v_pk_add_f32 v[2:3], v[2:3], v[6:7]
	v_lshlrev_b32_e32 v6, 16, v27
	v_and_b32_e32 v7, 0xffff0000, v27
	v_pk_add_f32 v[42:43], v[42:43], v[84:85]
	v_lshlrev_b32_e32 v84, 16, v28
	v_and_b32_e32 v85, 0xffff0000, v28
	v_pk_add_f32 v[2:3], v[2:3], v[6:7]
	v_lshlrev_b32_e32 v6, 16, v31
	v_and_b32_e32 v7, 0xffff0000, v31
	v_pk_add_f32 v[84:85], v[42:43], v[84:85]
	v_pk_add_f32 v[2:3], v[2:3], v[6:7]
	v_add_u32_e32 v68, 48, v49
	s_cbranch_execz .LBB0_255
	s_branch .LBB0_256
